# G2 mid-K rescale: both wave halves run the hook at the same time (extra barrier pair, like the aligned epilogue) instead of one after the other
# baseline (speedup 1.0000x reference)
; __device__ __forceinline__ float bflo(unsigned w) { return __uint_as_float(w << 16); }
; __device__ __forceinline__ float bfhi(unsigned w) { return __uint_as_float(w & 0xffff0000u); }
;     __device__ __forceinline__ void mid(f32x4 (&acc)[2][2][4][2], const Unit& u, int wr, int wc, int fr, int fq) const {
;         int row0 = u.pm * BM + wr * 64 + fr, col0 = u.pn * BM + wc * 32 + 8 * fq;
;         asm volatile("" : "+v"(row0), "+v"(col0));
; #pragma unroll
;         for (int ai = 0; ai < 2; ++ai)
; #pragma unroll
;             for (int m = 0; m < 4; ++m) { const size_t row = (size_t)(row0 + ai * HALF + m * 16);
; #pragma unroll
;                 for (int bj = 0; bj < 2; ++bj) { const int col = col0 + bj * HALF;
;                     const u32x4 ga = *(const u32x4*)(P + row * LDP + PC_GA + col), gb = *(const u32x4*)(P + row * LDP + PC_GB + col);
; #pragma unroll
;                     for (int j = 0; j < 2; ++j) {
;                         acc[ai][bj][m][0][2 * j] *= bflo(ga[j]) * __builtin_amdgcn_rcpf(bflo(gb[j])); acc[ai][bj][m][0][2 * j + 1] *= bfhi(ga[j]) * __builtin_amdgcn_rcpf(bfhi(gb[j]));
;                         acc[ai][bj][m][1][2 * j] *= bflo(ga[2 + j]) * __builtin_amdgcn_rcpf(bflo(gb[2 + j])); acc[ai][bj][m][1][2 * j + 1] *= bfhi(ga[2 + j]) * __builtin_amdgcn_rcpf(bfhi(gb[2 + j])); } }
;                 asm volatile("" ::: "memory"); }
.LBB0_78:
	s_cmpk_lg_i32 s60, 0x800
	s_cbranch_scc1 .LBB0_77
	s_and_b64 vcc, exec, s[44:45]
	s_cbranch_vccz .Lg2mid_a
	s_barrier
.Lg2mid_a:
	v_mul_u32_u24_e32 v161, 0x6200, v160
	v_lshl_add_u32 v161, v162, 1, v161
	s_add_u32 s62, s40, 0x4a00
	s_addc_u32 s63, s41, 0
	global_load_dwordx4 v[130:133], v161, s[62:63] offset:-2048
	global_load_dwordx4 v[134:137], v161, s[62:63] offset:2048
	s_add_u32 s62, s40, 0x4b00
	s_addc_u32 s63, s41, 0
	global_load_dwordx4 v[186:189], v161, s[62:63] offset:-2048
	global_load_dwordx4 v[190:193], v161, s[62:63] offset:2048
	s_add_u32 s62, s40, 0x66a00
	s_addc_u32 s63, s41, 0
	global_load_dwordx4 v[194:197], v161, s[62:63] offset:-2048
	global_load_dwordx4 v[198:201], v161, s[62:63] offset:2048
	s_add_u32 s62, s40, 0x66b00
	s_addc_u32 s63, s41, 0
	global_load_dwordx4 v[202:205], v161, s[62:63] offset:-2048
	global_load_dwordx4 v[206:209], v161, s[62:63] offset:2048
	s_add_u32 s62, s40, 0xc8a00
	s_addc_u32 s63, s41, 0
	global_load_dwordx4 v[214:217], v161, s[62:63] offset:-2048
	global_load_dwordx4 v[218:221], v161, s[62:63] offset:2048
	s_add_u32 s62, s40, 0xc8b00
	s_addc_u32 s63, s41, 0
	global_load_dwordx4 v[222:225], v161, s[62:63] offset:-2048
	global_load_dwordx4 v[226:229], v161, s[62:63] offset:2048
	s_add_u32 s62, s40, 0x12aa00
	s_addc_u32 s63, s41, 0
	global_load_dwordx4 v[230:233], v161, s[62:63] offset:-2048
	global_load_dwordx4 v[234:237], v161, s[62:63] offset:2048
	s_add_u32 s62, s40, 0x12ab00
	s_addc_u32 s63, s41, 0
	global_load_dwordx4 v[238:241], v161, s[62:63] offset:-2048
	global_load_dwordx4 v[242:245], v161, s[62:63] offset:2048
	s_waitcnt vmcnt(14)
	v_lshlrev_b32_e32 v144, 16, v134
	v_and_b32_e32 v145, 0xffff0000, v134
	v_lshlrev_b32_e32 v168, 16, v135
	v_and_b32_e32 v169, 0xffff0000, v135
	v_rcp_f32_e32 v144, v144
	v_rcp_f32_e32 v145, v145
	v_rcp_f32_e32 v168, v168
	v_rcp_f32_e32 v169, v169
	v_lshlrev_b32_e32 v142, 16, v130
	v_and_b32_e32 v143, 0xffff0000, v130
	v_pk_mul_f32 v[144:145], v[144:145], v[142:143]
	v_lshlrev_b32_e32 v142, 16, v131
	v_and_b32_e32 v143, 0xffff0000, v131
	v_pk_mul_f32 v[168:169], v[168:169], v[142:143]
	v_pk_mul_f32 v[126:127], v[126:127], v[144:145]
	v_pk_mul_f32 v[128:129], v[128:129], v[168:169]
	v_lshlrev_b32_e32 v144, 16, v136
	v_and_b32_e32 v145, 0xffff0000, v136
	v_lshlrev_b32_e32 v168, 16, v137
	v_and_b32_e32 v169, 0xffff0000, v137
	v_rcp_f32_e32 v144, v144
	v_rcp_f32_e32 v145, v145
	v_rcp_f32_e32 v168, v168
	v_rcp_f32_e32 v169, v169
	v_lshlrev_b32_e32 v142, 16, v132
	v_and_b32_e32 v143, 0xffff0000, v132
	v_pk_mul_f32 v[144:145], v[144:145], v[142:143]
	v_lshlrev_b32_e32 v142, 16, v133
	v_and_b32_e32 v143, 0xffff0000, v133
	v_pk_mul_f32 v[168:169], v[168:169], v[142:143]
	v_pk_mul_f32 v[122:123], v[122:123], v[144:145]
	v_pk_mul_f32 v[124:125], v[124:125], v[168:169]
	s_add_u32 s62, s40, 0x314a00
	s_addc_u32 s63, s41, 0
	global_load_dwordx4 v[130:133], v161, s[62:63] offset:-2048
	global_load_dwordx4 v[134:137], v161, s[62:63] offset:2048
	s_waitcnt vmcnt(14)
	v_lshlrev_b32_e32 v144, 16, v190
	v_and_b32_e32 v145, 0xffff0000, v190
	v_lshlrev_b32_e32 v168, 16, v191
	v_and_b32_e32 v169, 0xffff0000, v191
	v_rcp_f32_e32 v144, v144
	v_rcp_f32_e32 v145, v145
	v_rcp_f32_e32 v168, v168
	v_rcp_f32_e32 v169, v169
	v_lshlrev_b32_e32 v142, 16, v186
	v_and_b32_e32 v143, 0xffff0000, v186
	v_pk_mul_f32 v[144:145], v[144:145], v[142:143]
	v_lshlrev_b32_e32 v142, 16, v187
	v_and_b32_e32 v143, 0xffff0000, v187
	v_pk_mul_f32 v[168:169], v[168:169], v[142:143]
	v_pk_mul_f32 v[118:119], v[118:119], v[144:145]
	v_pk_mul_f32 v[120:121], v[120:121], v[168:169]
	v_lshlrev_b32_e32 v144, 16, v192
	v_and_b32_e32 v145, 0xffff0000, v192
	v_lshlrev_b32_e32 v168, 16, v193
	v_and_b32_e32 v169, 0xffff0000, v193
	v_rcp_f32_e32 v144, v144
	v_rcp_f32_e32 v145, v145
	v_rcp_f32_e32 v168, v168
	v_rcp_f32_e32 v169, v169
	v_lshlrev_b32_e32 v142, 16, v188
	v_and_b32_e32 v143, 0xffff0000, v188
	v_pk_mul_f32 v[144:145], v[144:145], v[142:143]
	v_lshlrev_b32_e32 v142, 16, v189
	v_and_b32_e32 v143, 0xffff0000, v189
	v_pk_mul_f32 v[168:169], v[168:169], v[142:143]
	v_pk_mul_f32 v[114:115], v[114:115], v[144:145]
	v_pk_mul_f32 v[116:117], v[116:117], v[168:169]
	s_add_u32 s62, s40, 0x314b00
	s_addc_u32 s63, s41, 0
	global_load_dwordx4 v[186:189], v161, s[62:63] offset:-2048
	global_load_dwordx4 v[190:193], v161, s[62:63] offset:2048
	s_waitcnt vmcnt(14)
	v_lshlrev_b32_e32 v144, 16, v198
	v_and_b32_e32 v145, 0xffff0000, v198
	v_lshlrev_b32_e32 v168, 16, v199
	v_and_b32_e32 v169, 0xffff0000, v199
	v_rcp_f32_e32 v144, v144
	v_rcp_f32_e32 v145, v145
	v_rcp_f32_e32 v168, v168
	v_rcp_f32_e32 v169, v169
	v_lshlrev_b32_e32 v142, 16, v194
	v_and_b32_e32 v143, 0xffff0000, v194
	v_pk_mul_f32 v[144:145], v[144:145], v[142:143]
	v_lshlrev_b32_e32 v142, 16, v195
	v_and_b32_e32 v143, 0xffff0000, v195
	v_pk_mul_f32 v[168:169], v[168:169], v[142:143]
	v_pk_mul_f32 v[110:111], v[110:111], v[144:145]
	v_pk_mul_f32 v[112:113], v[112:113], v[168:169]
	v_lshlrev_b32_e32 v144, 16, v200
	v_and_b32_e32 v145, 0xffff0000, v200
	v_lshlrev_b32_e32 v168, 16, v201
	v_and_b32_e32 v169, 0xffff0000, v201
	v_rcp_f32_e32 v144, v144
	v_rcp_f32_e32 v145, v145
	v_rcp_f32_e32 v168, v168
	v_rcp_f32_e32 v169, v169
	v_lshlrev_b32_e32 v142, 16, v196
	v_and_b32_e32 v143, 0xffff0000, v196
	v_pk_mul_f32 v[144:145], v[144:145], v[142:143]
	v_lshlrev_b32_e32 v142, 16, v197
	v_and_b32_e32 v143, 0xffff0000, v197
	v_pk_mul_f32 v[168:169], v[168:169], v[142:143]
	v_pk_mul_f32 v[106:107], v[106:107], v[144:145]
	v_pk_mul_f32 v[108:109], v[108:109], v[168:169]
	s_add_u32 s62, s40, 0x376a00
	s_addc_u32 s63, s41, 0
	global_load_dwordx4 v[194:197], v161, s[62:63] offset:-2048
	global_load_dwordx4 v[198:201], v161, s[62:63] offset:2048
	s_waitcnt vmcnt(14)
; __device__ __forceinline__ float bflo(unsigned w) { return __uint_as_float(w << 16); }
; __device__ __forceinline__ float bfhi(unsigned w) { return __uint_as_float(w & 0xffff0000u); }
;     __device__ __forceinline__ void mid(f32x4 (&acc)[2][2][4][2], const Unit& u, int wr, int wc, int fr, int fq) const {
;     ...
;                     const u32x4 ga = *(const u32x4*)(P + row * LDP + PC_GA + col), gb = *(const u32x4*)(P + row * LDP + PC_GB + col);
; #pragma unroll
;                     for (int j = 0; j < 2; ++j) {
;                         acc[ai][bj][m][0][2 * j] *= bflo(ga[j]) * __builtin_amdgcn_rcpf(bflo(gb[j])); acc[ai][bj][m][0][2 * j + 1] *= bfhi(ga[j]) * __builtin_amdgcn_rcpf(bfhi(gb[j]));
;                         acc[ai][bj][m][1][2 * j] *= bflo(ga[2 + j]) * __builtin_amdgcn_rcpf(bflo(gb[2 + j])); acc[ai][bj][m][1][2 * j + 1] *= bfhi(ga[2 + j]) * __builtin_amdgcn_rcpf(bfhi(gb[2 + j])); } }
	v_lshlrev_b32_e32 v144, 16, v206
	v_and_b32_e32 v145, 0xffff0000, v206
	v_lshlrev_b32_e32 v168, 16, v207
	v_and_b32_e32 v169, 0xffff0000, v207
	v_rcp_f32_e32 v144, v144
	v_rcp_f32_e32 v145, v145
	v_rcp_f32_e32 v168, v168
	v_rcp_f32_e32 v169, v169
	v_lshlrev_b32_e32 v142, 16, v202
	v_and_b32_e32 v143, 0xffff0000, v202
	v_pk_mul_f32 v[144:145], v[144:145], v[142:143]
	v_lshlrev_b32_e32 v142, 16, v203
	v_and_b32_e32 v143, 0xffff0000, v203
	v_pk_mul_f32 v[168:169], v[168:169], v[142:143]
	v_pk_mul_f32 v[102:103], v[102:103], v[144:145]
	v_pk_mul_f32 v[104:105], v[104:105], v[168:169]
	v_lshlrev_b32_e32 v144, 16, v208
	v_and_b32_e32 v145, 0xffff0000, v208
	v_lshlrev_b32_e32 v168, 16, v209
	v_and_b32_e32 v169, 0xffff0000, v209
	v_rcp_f32_e32 v144, v144
	v_rcp_f32_e32 v145, v145
	v_rcp_f32_e32 v168, v168
	v_rcp_f32_e32 v169, v169
	v_lshlrev_b32_e32 v142, 16, v204
	v_and_b32_e32 v143, 0xffff0000, v204
	v_pk_mul_f32 v[144:145], v[144:145], v[142:143]
	v_lshlrev_b32_e32 v142, 16, v205
	v_and_b32_e32 v143, 0xffff0000, v205
	v_pk_mul_f32 v[168:169], v[168:169], v[142:143]
	v_pk_mul_f32 v[98:99], v[98:99], v[144:145]
	v_pk_mul_f32 v[100:101], v[100:101], v[168:169]
	s_add_u32 s62, s40, 0x376b00
	s_addc_u32 s63, s41, 0
	global_load_dwordx4 v[202:205], v161, s[62:63] offset:-2048
	global_load_dwordx4 v[206:209], v161, s[62:63] offset:2048
	s_waitcnt vmcnt(14)
	v_lshlrev_b32_e32 v144, 16, v218
	v_and_b32_e32 v145, 0xffff0000, v218
	v_lshlrev_b32_e32 v168, 16, v219
	v_and_b32_e32 v169, 0xffff0000, v219
	v_rcp_f32_e32 v144, v144
	v_rcp_f32_e32 v145, v145
	v_rcp_f32_e32 v168, v168
	v_rcp_f32_e32 v169, v169
	v_lshlrev_b32_e32 v142, 16, v214
	v_and_b32_e32 v143, 0xffff0000, v214
	v_pk_mul_f32 v[144:145], v[144:145], v[142:143]
	v_lshlrev_b32_e32 v142, 16, v215
	v_and_b32_e32 v143, 0xffff0000, v215
	v_pk_mul_f32 v[168:169], v[168:169], v[142:143]
	v_pk_mul_f32 v[94:95], v[94:95], v[144:145]
	v_pk_mul_f32 v[96:97], v[96:97], v[168:169]
	v_lshlrev_b32_e32 v144, 16, v220
	v_and_b32_e32 v145, 0xffff0000, v220
	v_lshlrev_b32_e32 v168, 16, v221
	v_and_b32_e32 v169, 0xffff0000, v221
	v_rcp_f32_e32 v144, v144
	v_rcp_f32_e32 v145, v145
	v_rcp_f32_e32 v168, v168
	v_rcp_f32_e32 v169, v169
	v_lshlrev_b32_e32 v142, 16, v216
	v_and_b32_e32 v143, 0xffff0000, v216
	v_pk_mul_f32 v[144:145], v[144:145], v[142:143]
	v_lshlrev_b32_e32 v142, 16, v217
	v_and_b32_e32 v143, 0xffff0000, v217
	v_pk_mul_f32 v[168:169], v[168:169], v[142:143]
	v_pk_mul_f32 v[90:91], v[90:91], v[144:145]
	v_pk_mul_f32 v[92:93], v[92:93], v[168:169]
	s_add_u32 s62, s40, 0x3d8a00
	s_addc_u32 s63, s41, 0
	global_load_dwordx4 v[214:217], v161, s[62:63] offset:-2048
	global_load_dwordx4 v[218:221], v161, s[62:63] offset:2048
	s_waitcnt vmcnt(14)
	v_lshlrev_b32_e32 v144, 16, v226
	v_and_b32_e32 v145, 0xffff0000, v226
	v_lshlrev_b32_e32 v168, 16, v227
	v_and_b32_e32 v169, 0xffff0000, v227
	v_rcp_f32_e32 v144, v144
	v_rcp_f32_e32 v145, v145
	v_rcp_f32_e32 v168, v168
	v_rcp_f32_e32 v169, v169
	v_lshlrev_b32_e32 v142, 16, v222
	v_and_b32_e32 v143, 0xffff0000, v222
	v_pk_mul_f32 v[144:145], v[144:145], v[142:143]
	v_lshlrev_b32_e32 v142, 16, v223
	v_and_b32_e32 v143, 0xffff0000, v223
	v_pk_mul_f32 v[168:169], v[168:169], v[142:143]
	v_pk_mul_f32 v[86:87], v[86:87], v[144:145]
	v_pk_mul_f32 v[88:89], v[88:89], v[168:169]
	v_lshlrev_b32_e32 v144, 16, v228
	v_and_b32_e32 v145, 0xffff0000, v228
	v_lshlrev_b32_e32 v168, 16, v229
	v_and_b32_e32 v169, 0xffff0000, v229
	v_rcp_f32_e32 v144, v144
	v_rcp_f32_e32 v145, v145
	v_rcp_f32_e32 v168, v168
	v_rcp_f32_e32 v169, v169
	v_lshlrev_b32_e32 v142, 16, v224
	v_and_b32_e32 v143, 0xffff0000, v224
	v_pk_mul_f32 v[144:145], v[144:145], v[142:143]
	v_lshlrev_b32_e32 v142, 16, v225
	v_and_b32_e32 v143, 0xffff0000, v225
	v_pk_mul_f32 v[168:169], v[168:169], v[142:143]
	v_pk_mul_f32 v[82:83], v[82:83], v[144:145]
	v_pk_mul_f32 v[84:85], v[84:85], v[168:169]
	s_add_u32 s62, s40, 0x3d8b00
	s_addc_u32 s63, s41, 0
	global_load_dwordx4 v[222:225], v161, s[62:63] offset:-2048
	global_load_dwordx4 v[226:229], v161, s[62:63] offset:2048
	s_waitcnt vmcnt(14)
	v_lshlrev_b32_e32 v144, 16, v234
	v_and_b32_e32 v145, 0xffff0000, v234
	v_lshlrev_b32_e32 v168, 16, v235
	v_and_b32_e32 v169, 0xffff0000, v235
	v_rcp_f32_e32 v144, v144
	v_rcp_f32_e32 v145, v145
	v_rcp_f32_e32 v168, v168
	v_rcp_f32_e32 v169, v169
	v_lshlrev_b32_e32 v142, 16, v230
	v_and_b32_e32 v143, 0xffff0000, v230
	v_pk_mul_f32 v[144:145], v[144:145], v[142:143]
	v_lshlrev_b32_e32 v142, 16, v231
	v_and_b32_e32 v143, 0xffff0000, v231
	v_pk_mul_f32 v[168:169], v[168:169], v[142:143]
	v_pk_mul_f32 v[78:79], v[78:79], v[144:145]
	v_pk_mul_f32 v[80:81], v[80:81], v[168:169]
	v_lshlrev_b32_e32 v144, 16, v236
	v_and_b32_e32 v145, 0xffff0000, v236
	v_lshlrev_b32_e32 v168, 16, v237
	v_and_b32_e32 v169, 0xffff0000, v237
	v_rcp_f32_e32 v144, v144
	v_rcp_f32_e32 v145, v145
	v_rcp_f32_e32 v168, v168
	v_rcp_f32_e32 v169, v169
	v_lshlrev_b32_e32 v142, 16, v232
	v_and_b32_e32 v143, 0xffff0000, v232
	v_pk_mul_f32 v[144:145], v[144:145], v[142:143]
	v_lshlrev_b32_e32 v142, 16, v233
	v_and_b32_e32 v143, 0xffff0000, v233
	v_pk_mul_f32 v[168:169], v[168:169], v[142:143]
	v_pk_mul_f32 v[74:75], v[74:75], v[144:145]
	v_pk_mul_f32 v[76:77], v[76:77], v[168:169]
	s_add_u32 s62, s40, 0x43aa00
	s_addc_u32 s63, s41, 0
	global_load_dwordx4 v[230:233], v161, s[62:63] offset:-2048
	global_load_dwordx4 v[234:237], v161, s[62:63] offset:2048
	s_waitcnt vmcnt(14)
; __device__ __forceinline__ float bflo(unsigned w) { return __uint_as_float(w << 16); }
; __device__ __forceinline__ float bfhi(unsigned w) { return __uint_as_float(w & 0xffff0000u); }
;     __device__ __forceinline__ void mid(f32x4 (&acc)[2][2][4][2], const Unit& u, int wr, int wc, int fr, int fq) const {
;     ...
;                     const u32x4 ga = *(const u32x4*)(P + row * LDP + PC_GA + col), gb = *(const u32x4*)(P + row * LDP + PC_GB + col);
; #pragma unroll
;                     for (int j = 0; j < 2; ++j) {
;                         acc[ai][bj][m][0][2 * j] *= bflo(ga[j]) * __builtin_amdgcn_rcpf(bflo(gb[j])); acc[ai][bj][m][0][2 * j + 1] *= bfhi(ga[j]) * __builtin_amdgcn_rcpf(bfhi(gb[j]));
;                         acc[ai][bj][m][1][2 * j] *= bflo(ga[2 + j]) * __builtin_amdgcn_rcpf(bflo(gb[2 + j])); acc[ai][bj][m][1][2 * j + 1] *= bfhi(ga[2 + j]) * __builtin_amdgcn_rcpf(bfhi(gb[2 + j])); } }
	v_lshlrev_b32_e32 v144, 16, v242
	v_and_b32_e32 v145, 0xffff0000, v242
	v_lshlrev_b32_e32 v168, 16, v243
	v_and_b32_e32 v169, 0xffff0000, v243
	v_rcp_f32_e32 v144, v144
	v_rcp_f32_e32 v145, v145
	v_rcp_f32_e32 v168, v168
	v_rcp_f32_e32 v169, v169
	v_lshlrev_b32_e32 v142, 16, v238
	v_and_b32_e32 v143, 0xffff0000, v238
	v_pk_mul_f32 v[144:145], v[144:145], v[142:143]
	v_lshlrev_b32_e32 v142, 16, v239
	v_and_b32_e32 v143, 0xffff0000, v239
	v_pk_mul_f32 v[168:169], v[168:169], v[142:143]
	v_pk_mul_f32 v[70:71], v[70:71], v[144:145]
	v_pk_mul_f32 v[72:73], v[72:73], v[168:169]
	v_lshlrev_b32_e32 v144, 16, v244
	v_and_b32_e32 v145, 0xffff0000, v244
	v_lshlrev_b32_e32 v168, 16, v245
	v_and_b32_e32 v169, 0xffff0000, v245
	v_rcp_f32_e32 v144, v144
	v_rcp_f32_e32 v145, v145
	v_rcp_f32_e32 v168, v168
	v_rcp_f32_e32 v169, v169
	v_lshlrev_b32_e32 v142, 16, v240
	v_and_b32_e32 v143, 0xffff0000, v240
	v_pk_mul_f32 v[144:145], v[144:145], v[142:143]
	v_lshlrev_b32_e32 v142, 16, v241
	v_and_b32_e32 v143, 0xffff0000, v241
	v_pk_mul_f32 v[168:169], v[168:169], v[142:143]
	v_pk_mul_f32 v[66:67], v[66:67], v[144:145]
	v_pk_mul_f32 v[68:69], v[68:69], v[168:169]
	s_add_u32 s62, s40, 0x43ab00
	s_addc_u32 s63, s41, 0
	global_load_dwordx4 v[238:241], v161, s[62:63] offset:-2048
	global_load_dwordx4 v[242:245], v161, s[62:63] offset:2048
	s_waitcnt vmcnt(14)
	v_lshlrev_b32_e32 v144, 16, v134
	v_and_b32_e32 v145, 0xffff0000, v134
	v_lshlrev_b32_e32 v168, 16, v135
	v_and_b32_e32 v169, 0xffff0000, v135
	v_rcp_f32_e32 v144, v144
	v_rcp_f32_e32 v145, v145
	v_rcp_f32_e32 v168, v168
	v_rcp_f32_e32 v169, v169
	v_lshlrev_b32_e32 v142, 16, v130
	v_and_b32_e32 v143, 0xffff0000, v130
	v_pk_mul_f32 v[144:145], v[144:145], v[142:143]
	v_lshlrev_b32_e32 v142, 16, v131
	v_and_b32_e32 v143, 0xffff0000, v131
	v_pk_mul_f32 v[168:169], v[168:169], v[142:143]
	v_pk_mul_f32 v[62:63], v[62:63], v[144:145]
	v_pk_mul_f32 v[64:65], v[64:65], v[168:169]
	v_lshlrev_b32_e32 v144, 16, v136
	v_and_b32_e32 v145, 0xffff0000, v136
	v_lshlrev_b32_e32 v168, 16, v137
	v_and_b32_e32 v169, 0xffff0000, v137
	v_rcp_f32_e32 v144, v144
	v_rcp_f32_e32 v145, v145
	v_rcp_f32_e32 v168, v168
	v_rcp_f32_e32 v169, v169
	v_lshlrev_b32_e32 v142, 16, v132
	v_and_b32_e32 v143, 0xffff0000, v132
	v_pk_mul_f32 v[144:145], v[144:145], v[142:143]
	v_lshlrev_b32_e32 v142, 16, v133
	v_and_b32_e32 v143, 0xffff0000, v133
	v_pk_mul_f32 v[168:169], v[168:169], v[142:143]
	v_pk_mul_f32 v[58:59], v[58:59], v[144:145]
	v_pk_mul_f32 v[60:61], v[60:61], v[168:169]
	s_waitcnt vmcnt(12)
	v_lshlrev_b32_e32 v144, 16, v190
	v_and_b32_e32 v145, 0xffff0000, v190
	v_lshlrev_b32_e32 v168, 16, v191
	v_and_b32_e32 v169, 0xffff0000, v191
	v_rcp_f32_e32 v144, v144
	v_rcp_f32_e32 v145, v145
	v_rcp_f32_e32 v168, v168
	v_rcp_f32_e32 v169, v169
	v_lshlrev_b32_e32 v142, 16, v186
	v_and_b32_e32 v143, 0xffff0000, v186
	v_pk_mul_f32 v[144:145], v[144:145], v[142:143]
	v_lshlrev_b32_e32 v142, 16, v187
	v_and_b32_e32 v143, 0xffff0000, v187
	v_pk_mul_f32 v[168:169], v[168:169], v[142:143]
	v_pk_mul_f32 v[54:55], v[54:55], v[144:145]
	v_pk_mul_f32 v[56:57], v[56:57], v[168:169]
	v_lshlrev_b32_e32 v144, 16, v192
	v_and_b32_e32 v145, 0xffff0000, v192
	v_lshlrev_b32_e32 v168, 16, v193
	v_and_b32_e32 v169, 0xffff0000, v193
	v_rcp_f32_e32 v144, v144
	v_rcp_f32_e32 v145, v145
	v_rcp_f32_e32 v168, v168
	v_rcp_f32_e32 v169, v169
	v_lshlrev_b32_e32 v142, 16, v188
	v_and_b32_e32 v143, 0xffff0000, v188
	v_pk_mul_f32 v[144:145], v[144:145], v[142:143]
	v_lshlrev_b32_e32 v142, 16, v189
	v_and_b32_e32 v143, 0xffff0000, v189
	v_pk_mul_f32 v[168:169], v[168:169], v[142:143]
	v_pk_mul_f32 v[50:51], v[50:51], v[144:145]
	v_pk_mul_f32 v[52:53], v[52:53], v[168:169]
	s_waitcnt vmcnt(10)
	v_lshlrev_b32_e32 v144, 16, v198
	v_and_b32_e32 v145, 0xffff0000, v198
	v_lshlrev_b32_e32 v168, 16, v199
	v_and_b32_e32 v169, 0xffff0000, v199
	v_rcp_f32_e32 v144, v144
	v_rcp_f32_e32 v145, v145
	v_rcp_f32_e32 v168, v168
	v_rcp_f32_e32 v169, v169
	v_lshlrev_b32_e32 v142, 16, v194
	v_and_b32_e32 v143, 0xffff0000, v194
	v_pk_mul_f32 v[144:145], v[144:145], v[142:143]
	v_lshlrev_b32_e32 v142, 16, v195
	v_and_b32_e32 v143, 0xffff0000, v195
	v_pk_mul_f32 v[168:169], v[168:169], v[142:143]
	v_pk_mul_f32 v[46:47], v[46:47], v[144:145]
	v_pk_mul_f32 v[48:49], v[48:49], v[168:169]
	v_lshlrev_b32_e32 v144, 16, v200
	v_and_b32_e32 v145, 0xffff0000, v200
	v_lshlrev_b32_e32 v168, 16, v201
	v_and_b32_e32 v169, 0xffff0000, v201
	v_rcp_f32_e32 v144, v144
	v_rcp_f32_e32 v145, v145
	v_rcp_f32_e32 v168, v168
	v_rcp_f32_e32 v169, v169
	v_lshlrev_b32_e32 v142, 16, v196
	v_and_b32_e32 v143, 0xffff0000, v196
	v_pk_mul_f32 v[144:145], v[144:145], v[142:143]
	v_lshlrev_b32_e32 v142, 16, v197
	v_and_b32_e32 v143, 0xffff0000, v197
	v_pk_mul_f32 v[168:169], v[168:169], v[142:143]
	v_pk_mul_f32 v[42:43], v[42:43], v[144:145]
	v_pk_mul_f32 v[44:45], v[44:45], v[168:169]
	s_waitcnt vmcnt(8)
	v_lshlrev_b32_e32 v144, 16, v206
	v_and_b32_e32 v145, 0xffff0000, v206
	v_lshlrev_b32_e32 v168, 16, v207
	v_and_b32_e32 v169, 0xffff0000, v207
	v_rcp_f32_e32 v144, v144
	v_rcp_f32_e32 v145, v145
	v_rcp_f32_e32 v168, v168
	v_rcp_f32_e32 v169, v169
	v_lshlrev_b32_e32 v142, 16, v202
	v_and_b32_e32 v143, 0xffff0000, v202
	v_pk_mul_f32 v[144:145], v[144:145], v[142:143]
	v_lshlrev_b32_e32 v142, 16, v203
	v_and_b32_e32 v143, 0xffff0000, v203
	v_pk_mul_f32 v[168:169], v[168:169], v[142:143]
	v_pk_mul_f32 v[38:39], v[38:39], v[144:145]
	v_pk_mul_f32 v[40:41], v[40:41], v[168:169]
	v_lshlrev_b32_e32 v144, 16, v208
	v_and_b32_e32 v145, 0xffff0000, v208
	v_lshlrev_b32_e32 v168, 16, v209
	v_and_b32_e32 v169, 0xffff0000, v209
	v_rcp_f32_e32 v144, v144
	v_rcp_f32_e32 v145, v145
	v_rcp_f32_e32 v168, v168
	v_rcp_f32_e32 v169, v169
	v_lshlrev_b32_e32 v142, 16, v204
	v_and_b32_e32 v143, 0xffff0000, v204
	v_pk_mul_f32 v[144:145], v[144:145], v[142:143]
	v_lshlrev_b32_e32 v142, 16, v205
	v_and_b32_e32 v143, 0xffff0000, v205
	v_pk_mul_f32 v[168:169], v[168:169], v[142:143]
	v_pk_mul_f32 v[34:35], v[34:35], v[144:145]
	v_pk_mul_f32 v[36:37], v[36:37], v[168:169]
	s_waitcnt vmcnt(6)
; __device__ __forceinline__ float bflo(unsigned w) { return __uint_as_float(w << 16); }
; __device__ __forceinline__ float bfhi(unsigned w) { return __uint_as_float(w & 0xffff0000u); }
; #define PG8_BAR __builtin_amdgcn_s_barrier()
;     __device__ __forceinline__ void mid(f32x4 (&acc)[2][2][4][2], const Unit& u, int wr, int wc, int fr, int fq) const {
;     ...
;                     const u32x4 ga = *(const u32x4*)(P + row * LDP + PC_GA + col), gb = *(const u32x4*)(P + row * LDP + PC_GB + col);
; #pragma unroll
;                     for (int j = 0; j < 2; ++j) {
;                         acc[ai][bj][m][0][2 * j] *= bflo(ga[j]) * __builtin_amdgcn_rcpf(bflo(gb[j])); acc[ai][bj][m][0][2 * j + 1] *= bfhi(ga[j]) * __builtin_amdgcn_rcpf(bfhi(gb[j]));
;                         acc[ai][bj][m][1][2 * j] *= bflo(ga[2 + j]) * __builtin_amdgcn_rcpf(bflo(gb[2 + j])); acc[ai][bj][m][1][2 * j + 1] *= bfhi(ga[2 + j]) * __builtin_amdgcn_rcpf(bfhi(gb[2 + j])); } }
;                 asm volatile("" ::: "memory"); }
; template <class Epi, class Sched, bool ALIGN_EPI = false, bool SP2 = false>
; __device__ __forceinline__ void gemm_phase(PG8_LAS unsigned char* lds, const Gemm g, const Sched& S, const Epi& E) {
;     ...
;         if constexpr (ALIGN_EPI) { if (wr == 0) PG8_BAR; }
	v_lshlrev_b32_e32 v144, 16, v218
	v_and_b32_e32 v145, 0xffff0000, v218
	v_lshlrev_b32_e32 v168, 16, v219
	v_and_b32_e32 v169, 0xffff0000, v219
	v_rcp_f32_e32 v144, v144
	v_rcp_f32_e32 v145, v145
	v_rcp_f32_e32 v168, v168
	v_rcp_f32_e32 v169, v169
	v_lshlrev_b32_e32 v142, 16, v214
	v_and_b32_e32 v143, 0xffff0000, v214
	v_pk_mul_f32 v[144:145], v[144:145], v[142:143]
	v_lshlrev_b32_e32 v142, 16, v215
	v_and_b32_e32 v143, 0xffff0000, v215
	v_pk_mul_f32 v[168:169], v[168:169], v[142:143]
	v_pk_mul_f32 v[30:31], v[30:31], v[144:145]
	v_pk_mul_f32 v[32:33], v[32:33], v[168:169]
	v_lshlrev_b32_e32 v144, 16, v220
	v_and_b32_e32 v145, 0xffff0000, v220
	v_lshlrev_b32_e32 v168, 16, v221
	v_and_b32_e32 v169, 0xffff0000, v221
	v_rcp_f32_e32 v144, v144
	v_rcp_f32_e32 v145, v145
	v_rcp_f32_e32 v168, v168
	v_rcp_f32_e32 v169, v169
	v_lshlrev_b32_e32 v142, 16, v216
	v_and_b32_e32 v143, 0xffff0000, v216
	v_pk_mul_f32 v[144:145], v[144:145], v[142:143]
	v_lshlrev_b32_e32 v142, 16, v217
	v_and_b32_e32 v143, 0xffff0000, v217
	v_pk_mul_f32 v[168:169], v[168:169], v[142:143]
	v_pk_mul_f32 v[26:27], v[26:27], v[144:145]
	v_pk_mul_f32 v[28:29], v[28:29], v[168:169]
	s_waitcnt vmcnt(4)
	v_lshlrev_b32_e32 v144, 16, v226
	v_and_b32_e32 v145, 0xffff0000, v226
	v_lshlrev_b32_e32 v168, 16, v227
	v_and_b32_e32 v169, 0xffff0000, v227
	v_rcp_f32_e32 v144, v144
	v_rcp_f32_e32 v145, v145
	v_rcp_f32_e32 v168, v168
	v_rcp_f32_e32 v169, v169
	v_lshlrev_b32_e32 v142, 16, v222
	v_and_b32_e32 v143, 0xffff0000, v222
	v_pk_mul_f32 v[144:145], v[144:145], v[142:143]
	v_lshlrev_b32_e32 v142, 16, v223
	v_and_b32_e32 v143, 0xffff0000, v223
	v_pk_mul_f32 v[168:169], v[168:169], v[142:143]
	v_pk_mul_f32 v[22:23], v[22:23], v[144:145]
	v_pk_mul_f32 v[24:25], v[24:25], v[168:169]
	v_lshlrev_b32_e32 v144, 16, v228
	v_and_b32_e32 v145, 0xffff0000, v228
	v_lshlrev_b32_e32 v168, 16, v229
	v_and_b32_e32 v169, 0xffff0000, v229
	v_rcp_f32_e32 v144, v144
	v_rcp_f32_e32 v145, v145
	v_rcp_f32_e32 v168, v168
	v_rcp_f32_e32 v169, v169
	v_lshlrev_b32_e32 v142, 16, v224
	v_and_b32_e32 v143, 0xffff0000, v224
	v_pk_mul_f32 v[144:145], v[144:145], v[142:143]
	v_lshlrev_b32_e32 v142, 16, v225
	v_and_b32_e32 v143, 0xffff0000, v225
	v_pk_mul_f32 v[168:169], v[168:169], v[142:143]
	v_pk_mul_f32 v[18:19], v[18:19], v[144:145]
	v_pk_mul_f32 v[20:21], v[20:21], v[168:169]
	s_waitcnt vmcnt(2)
	v_lshlrev_b32_e32 v144, 16, v234
	v_and_b32_e32 v145, 0xffff0000, v234
	v_lshlrev_b32_e32 v168, 16, v235
	v_and_b32_e32 v169, 0xffff0000, v235
	v_rcp_f32_e32 v144, v144
	v_rcp_f32_e32 v145, v145
	v_rcp_f32_e32 v168, v168
	v_rcp_f32_e32 v169, v169
	v_lshlrev_b32_e32 v142, 16, v230
	v_and_b32_e32 v143, 0xffff0000, v230
	v_pk_mul_f32 v[144:145], v[144:145], v[142:143]
	v_lshlrev_b32_e32 v142, 16, v231
	v_and_b32_e32 v143, 0xffff0000, v231
	v_pk_mul_f32 v[168:169], v[168:169], v[142:143]
	v_pk_mul_f32 v[14:15], v[14:15], v[144:145]
	v_pk_mul_f32 v[16:17], v[16:17], v[168:169]
	v_lshlrev_b32_e32 v144, 16, v236
	v_and_b32_e32 v145, 0xffff0000, v236
	v_lshlrev_b32_e32 v168, 16, v237
	v_and_b32_e32 v169, 0xffff0000, v237
	v_rcp_f32_e32 v144, v144
	v_rcp_f32_e32 v145, v145
	v_rcp_f32_e32 v168, v168
	v_rcp_f32_e32 v169, v169
	v_lshlrev_b32_e32 v142, 16, v232
	v_and_b32_e32 v143, 0xffff0000, v232
	v_pk_mul_f32 v[144:145], v[144:145], v[142:143]
	v_lshlrev_b32_e32 v142, 16, v233
	v_and_b32_e32 v143, 0xffff0000, v233
	v_pk_mul_f32 v[168:169], v[168:169], v[142:143]
	v_pk_mul_f32 v[10:11], v[10:11], v[144:145]
	v_pk_mul_f32 v[12:13], v[12:13], v[168:169]
	s_waitcnt vmcnt(0)
	v_lshlrev_b32_e32 v144, 16, v242
	v_and_b32_e32 v145, 0xffff0000, v242
	v_lshlrev_b32_e32 v168, 16, v243
	v_and_b32_e32 v169, 0xffff0000, v243
	v_rcp_f32_e32 v144, v144
	v_rcp_f32_e32 v145, v145
	v_rcp_f32_e32 v168, v168
	v_rcp_f32_e32 v169, v169
	v_lshlrev_b32_e32 v142, 16, v238
	v_and_b32_e32 v143, 0xffff0000, v238
	v_pk_mul_f32 v[144:145], v[144:145], v[142:143]
	v_lshlrev_b32_e32 v142, 16, v239
	v_and_b32_e32 v143, 0xffff0000, v239
	v_pk_mul_f32 v[168:169], v[168:169], v[142:143]
	v_pk_mul_f32 v[6:7], v[6:7], v[144:145]
	v_pk_mul_f32 v[8:9], v[8:9], v[168:169]
	v_lshlrev_b32_e32 v144, 16, v244
	v_and_b32_e32 v145, 0xffff0000, v244
	v_lshlrev_b32_e32 v168, 16, v245
	v_and_b32_e32 v169, 0xffff0000, v245
	v_rcp_f32_e32 v144, v144
	v_rcp_f32_e32 v145, v145
	v_rcp_f32_e32 v168, v168
	v_rcp_f32_e32 v169, v169
	v_lshlrev_b32_e32 v142, 16, v240
	v_and_b32_e32 v143, 0xffff0000, v240
	v_pk_mul_f32 v[144:145], v[144:145], v[142:143]
	v_lshlrev_b32_e32 v142, 16, v241
	v_and_b32_e32 v143, 0xffff0000, v241
	v_pk_mul_f32 v[168:169], v[168:169], v[142:143]
	v_pk_mul_f32 v[2:3], v[2:3], v[144:145]
	v_pk_mul_f32 v[4:5], v[4:5], v[168:169]
	s_andn2_b64 vcc, exec, s[44:45]
	s_cbranch_vccz .Lg2mid_b
	s_barrier
.Lg2mid_b:
	s_branch .LBB0_77
.LBB0_80:
	v_readlane_b32 s78, v253, 49
	s_and_b64 vcc, exec, s[44:45]
	s_mov_b32 s76, 0x1ffff
	v_readlane_b32 s79, v253, 50
	s_cbranch_vccz .LBB0_82
	s_barrier
